# adds: x->bf16 prologue loop issues its four row loads together (counted waits) instead of load/wait/store x4
# baseline (speedup 1.0000x reference)
.LBB0_1938:
	global_load_dwordx4 v[20:23], v[12:13], off
	global_load_dwordx4 v[24:27], v[12:13], off offset:1024
	global_load_dwordx4 v[28:31], v[12:13], off offset:2048
	global_load_dwordx4 v[32:35], v[12:13], off offset:3072
	s_waitcnt vmcnt(3)
	v_cvt_pk_bf16_f32 v66, v20, v21
	v_cvt_pk_bf16_f32 v67, v22, v23
	global_store_dwordx2 v[10:11], v[66:67], off offset:-1024
	v_mul_f32_e32 v0, v21, v21
	s_waitcnt lgkmcnt(0)
	v_mul_f32_e32 v3, v23, v23
	v_fmac_f32_e32 v0, v20, v20
	v_fmac_f32_e32 v3, v22, v22
	v_add_f32_e32 v0, v0, v3
	s_waitcnt vmcnt(3)
	v_cvt_pk_bf16_f32 v68, v24, v25
	v_cvt_pk_bf16_f32 v69, v26, v27
	global_store_dwordx2 v[10:11], v[68:69], off offset:-512
	v_mul_f32_e32 v3, v25, v25
	v_mul_f32_e32 v20, v27, v27
	v_fmac_f32_e32 v3, v24, v24
	v_fmac_f32_e32 v20, v26, v26
	v_add_f32_e32 v3, v3, v20
	v_add_f32_e32 v0, v0, v3
	s_waitcnt vmcnt(3)
	v_cvt_pk_bf16_f32 v70, v28, v29
	v_cvt_pk_bf16_f32 v71, v30, v31
	global_store_dwordx2 v[10:11], v[70:71], off
	v_mul_f32_e32 v3, v29, v29
	v_mul_f32_e32 v20, v31, v31
	v_fmac_f32_e32 v3, v28, v28
	v_fmac_f32_e32 v20, v30, v30
	v_add_f32_e32 v3, v3, v20
	v_add_f32_e32 v0, v0, v3
	s_waitcnt vmcnt(3)
	v_mul_f32_e32 v3, v33, v33
	v_mul_f32_e32 v20, v35, v35
	v_fmac_f32_e32 v3, v32, v32
	v_fmac_f32_e32 v20, v34, v34
	v_add_f32_e32 v3, v3, v20
	v_add_f32_e32 v0, v0, v3
	ds_bpermute_b32 v3, v14, v0
	v_cvt_pk_bf16_f32 v20, v32, v33
	v_cvt_pk_bf16_f32 v21, v34, v35
	global_store_dwordx2 v[10:11], v[20:21], off offset:512
	s_waitcnt lgkmcnt(0)
	v_add_f32_e32 v0, v0, v3
	ds_bpermute_b32 v3, v15, v0
	s_waitcnt lgkmcnt(0)
	v_add_f32_e32 v0, v0, v3
	ds_bpermute_b32 v3, v16, v0
	s_waitcnt lgkmcnt(0)
	v_add_f32_e32 v0, v0, v3
	ds_bpermute_b32 v3, v17, v0
	s_waitcnt lgkmcnt(0)
	v_add_f32_e32 v0, v0, v3
	ds_bpermute_b32 v3, v18, v0
	s_waitcnt lgkmcnt(0)
	v_add_f32_e32 v0, v0, v3
	ds_bpermute_b32 v3, v19, v0
	s_and_saveexec_b64 s[4:5], vcc
	s_cbranch_execz .LBB0_1937
	s_waitcnt lgkmcnt(0)
	v_add_f32_e32 v0, v0, v3
	v_cndmask_b32_e64 v0, 0, v0, s[0:1]
	global_store_dword v[8:9], v0, off
	s_branch .LBB0_1937
